# c6 + retention output stores through one scalar base and 32-bit lane offsets (saddr form), fewer 64-bit VALU address ops
# speedup vs baseline: 1.0086x; 1.0007x over previous
; #define LAS __attribute__((address_space(3)))
; DI unsigned pack_bf16(float lo, float hi) { f32v2 f = {lo, hi}; bf16v2 b = __builtin_convertvector(f, bf16v2); return __builtin_bit_cast(unsigned, b); }
; DI s16x4 lds_tr(LAS unsigned char* L, int off) { return __builtin_amdgcn_ds_read_tr16_b64_v4i16((LAS s16x4*)(L + off)); }
; DI bf16x8 cat4(s16x4 lo, s16x4 hi) { return __builtin_shufflevector(lo, hi, 0, 1, 2, 3, 4, 5, 6, 7); }
; DI f32x4 mfma16(bf16x8 a, bf16x8 b, f32x4 c) { return __builtin_amdgcn_mfma_f32_16x16x32_bf16(a, b, c, 0, 0, 0); }
; DI void ret_phase(LAS unsigned char* L, const bf16_t* P, bf16_t* R, const float* lg2tab, int nseq) {
;     ...
;             for (int s = 0; s < 2; ++s) {
;                 const int kr = 32 * s + 8 * quad + q4, ko = (32 * s + 8 * quad) * 2;
;                 const bf16x8 bv = cat4(lds_tr(L, RT_OV + cur * 64 * RT_RSV + kr * RT_RSV + (xb * 16 + 4 * p4) * 2), lds_tr(L, RT_OV + cur * 64 * RT_RSV + (kr + 4) * RT_RSV + (xb * 16 + 4 * p4) * 2));
;                 const bf16x8 a0 = lds_r128(L, RT_OP + ((2 * wh) * 16 + l15) * RT_RSV + ko), a1 = lds_r128(L, RT_OP + ((2 * wh + 1) * 16 + l15) * RT_RSV + ko);
;                 o0 = mfma16(a0, bv, o0); o1 = mfma16(a1, bv, o1);
;             }
; #pragma unroll
;             for (int t = 0; t < 2; ++t)
; #pragma unroll
;                 for (int r = 0; r < 4; ++r) {
;                     const int q = (2 * wh + t) * 16 + 4 * quad + r;
;                     const float val = t ? o1[r] : o0[r];
;                     rout[(tokbase + (size_t)c * 64 + q) * RMIX + xb * 16 + l15] = (bf16_t)(pack_bf16(val, 0.f) & 0xffffu);
;                 }
; #pragma unroll
;             for (int j = 0; j < 8; ++j) { const int db = 8 * wh + j; u32x2 w; w.x = pack_bf16(st[j][0], st[j][1]); w.y = pack_bf16(st[j][2], st[j][3]);
;                 *(LAS u32x2*)(L + RT_OS + (xb * 16 + l15) * RT_RSQ + (db * 16 + 4 * quad) * 2) = w; }
;             __syncthreads();
.LBB0_895:
	s_mulk_i32 s24, 0x2400
	v_mov_b32_e32 v78, s25
	s_add_i32 s24, s24, 0
	v_cndmask_b32_e64 v0, v0, v78, s[8:9]
	s_add_i32 s24, s24, 0x18c00
	v_add_u32_e32 v78, 0, v190
	v_add_u32_e32 v92, s24, v82
	v_add_u32_e32 v93, 0x1f800, v78
	v_add_u32_e32 v94, 0x20100, v78
	v_add_u32_e32 v78, v92, v83
	v_add3_u32 v80, s24, v83, v82
	v_add_u32_e32 v83, v93, v186
	ds_read_b128 v[84:87], v83
	v_add_u32_e32 v83, v94, v186
	ds_read_b128 v[88:91], v83
	ds_read_b64_tr_b16 v[78:79], v78
	ds_read_b64_tr_b16 v[80:81], v80 offset:576
	v_pk_mul_f32 v[72:73], v[138:139], v[72:73]
	v_pk_mul_f32 v[70:71], v[136:137], v[70:71]
	v_pk_mul_f32 v[76:77], v[142:143], v[76:77]
	v_pk_mul_f32 v[74:75], v[140:141], v[74:75]
	s_waitcnt lgkmcnt(0)
	v_mfma_f32_16x16x32_bf16 v[70:73], v[84:87], v[78:81], v[70:73]
	v_lshlrev_b32_e32 v0, 6, v0
	s_add_i32 s27, s27, -1
	s_add_i32 s26, s26, 1
	v_mfma_f32_16x16x32_bf16 v[74:77], v[88:91], v[78:81], v[74:77]
	v_add_u32_e32 v78, 32, v187
	v_or_b32_e32 v79, v78, v189
	v_lshlrev_b32_e32 v86, 1, v78
	v_mul_lo_u32 v80, v79, s91
	v_add_u32_e32 v78, v92, v80
	v_add3_u32 v80, s24, v80, v82
	v_add_u32_e32 v82, v93, v86
	v_add_u32_e32 v86, v94, v86
	ds_read_b128 v[82:85], v82
	ds_read_b128 v[86:89], v86
	ds_read_b64_tr_b16 v[78:79], v78
	ds_read_b64_tr_b16 v[80:81], v80 offset:576
	s_waitcnt lgkmcnt(0)
	v_mfma_f32_16x16x32_bf16 v[70:73], v[82:85], v[78:81], v[70:73]
	v_mfma_f32_16x16x32_bf16 v[74:77], v[86:89], v[78:81], v[74:77]
	v_readfirstlane_b32 s100, v0
	s_add_u32 s100, s12, s100
	s_addc_u32 s101, s13, 0
	s_lshl_b64 s[100:101], s[100:101], 12
	s_add_u32 s100, s100, s18
	s_addc_u32 s101, s101, s19
	s_cmp_eq_u32 s27, -2
	v_lshl_add_u32 v78, v188, 2, s31
	v_lshlrev_b32_e32 v0, 1, v185
	v_lshl_add_u32 v78, v78, 12, v0
	v_cvt_pk_bf16_f32 v0, v70, s0
	global_store_short v78, v0, s[100:101]
	v_add_u32_e32 v79, 0x1000, v78
	v_cvt_pk_bf16_f32 v0, v71, s0
	global_store_short v79, v0, s[100:101]
	v_add_u32_e32 v79, 0x2000, v78
	v_cvt_pk_bf16_f32 v0, v72, s0
	global_store_short v79, v0, s[100:101]
	v_add_u32_e32 v79, 0x3000, v78
	v_cvt_pk_bf16_f32 v0, v73, s0
	global_store_short v79, v0, s[100:101]
	v_add_u32_e32 v79, 0x10000, v78
	v_cvt_pk_bf16_f32 v0, v74, s0
	global_store_short v79, v0, s[100:101]
	v_add_u32_e32 v79, 0x11000, v78
	v_cvt_pk_bf16_f32 v0, v75, s0
	global_store_short v79, v0, s[100:101]
	v_add_u32_e32 v79, 0x12000, v78
	v_cvt_pk_bf16_f32 v0, v76, s0
	global_store_short v79, v0, s[100:101]
	v_add_u32_e32 v79, 0x13000, v78
	v_cvt_pk_bf16_f32 v0, v77, s0
	global_store_short v79, v0, s[100:101]
	v_add_u32_e32 v0, s78, v184
	v_add3_u32 v0, v0, v187, s37
	v_cvt_pk_bf16_f32 v70, v38, v39
	v_cvt_pk_bf16_f32 v71, v40, v41
	v_cvt_pk_bf16_f32 v72, v62, v63
	v_cvt_pk_bf16_f32 v73, v64, v65
	ds_write2_b64 v0, v[70:71], v[72:73] offset1:4
	v_cvt_pk_bf16_f32 v70, v54, v55
	v_cvt_pk_bf16_f32 v71, v56, v57
	v_cvt_pk_bf16_f32 v72, v50, v51
	v_cvt_pk_bf16_f32 v73, v52, v53
	ds_write2_b64 v0, v[70:71], v[72:73] offset0:8 offset1:12
	v_cvt_pk_bf16_f32 v70, v58, v59
	v_cvt_pk_bf16_f32 v71, v60, v61
	v_cvt_pk_bf16_f32 v72, v66, v67
	v_cvt_pk_bf16_f32 v73, v68, v69
	ds_write2_b64 v0, v[70:71], v[72:73] offset0:16 offset1:20
	v_cvt_pk_bf16_f32 v70, v46, v47
	v_cvt_pk_bf16_f32 v71, v48, v49
	v_cvt_pk_bf16_f32 v72, v42, v43
	v_cvt_pk_bf16_f32 v73, v44, v45
	ds_write2_b64 v0, v[70:71], v[72:73] offset0:24 offset1:28
	s_waitcnt lgkmcnt(0)
	s_barrier
	s_cbranch_scc1 .LBB0_890

; __global__ void __launch_bounds__(NTHR, 2) mega_fwd(Params p) {
;     extern __shared__ __attribute__((aligned(16))) unsigned char shm[];
	.amdhsa_kernel _Z8mega_fwd6Params
		.amdhsa_group_segment_fixed_size 0
		.amdhsa_private_segment_fixed_size 0
		.amdhsa_kernarg_size 400
		.amdhsa_user_sgpr_count 2
		.amdhsa_user_sgpr_dispatch_ptr 0
		.amdhsa_user_sgpr_queue_ptr 0
		.amdhsa_user_sgpr_kernarg_segment_ptr 1
		.amdhsa_user_sgpr_dispatch_id 0
		.amdhsa_user_sgpr_kernarg_preload_length 0
		.amdhsa_user_sgpr_kernarg_preload_offset 0
		.amdhsa_user_sgpr_private_segment_size 0
		.amdhsa_uses_dynamic_stack 0
		.amdhsa_enable_private_segment 0
		.amdhsa_system_sgpr_workgroup_id_x 1
		.amdhsa_system_sgpr_workgroup_id_y 0
		.amdhsa_system_sgpr_workgroup_id_z 0
		.amdhsa_system_sgpr_workgroup_info 0
		.amdhsa_system_vgpr_workitem_id 2
		.amdhsa_next_free_vgpr 256
		.amdhsa_next_free_sgpr 102
		.amdhsa_accum_offset 256
		.amdhsa_reserve_vcc 1
		.amdhsa_float_round_mode_32 0
		.amdhsa_float_round_mode_16_64 0
		.amdhsa_float_denorm_mode_32 3
		.amdhsa_float_denorm_mode_16_64 3
		.amdhsa_dx10_clamp 1
		.amdhsa_ieee_mode 1
		.amdhsa_fp16_overflow 0
		.amdhsa_tg_split 0
		.amdhsa_exception_fp_ieee_invalid_op 0
		.amdhsa_exception_fp_denorm_src 0
		.amdhsa_exception_fp_ieee_div_zero 0
		.amdhsa_exception_fp_ieee_overflow 0
		.amdhsa_exception_fp_ieee_underflow 0
		.amdhsa_exception_fp_ieee_inexact 0
		.amdhsa_exception_int_div_zero 0
	.end_amdhsa_kernel

amdhsa.kernels:
  - .agpr_count:     0
    .args:
      - .offset:         0
        .size:           144
        .value_kind:     by_value
      - .offset:         144
        .size:           4
        .value_kind:     hidden_block_count_x
      - .offset:         148
        .size:           4
        .value_kind:     hidden_block_count_y
      - .offset:         152
        .size:           4
        .value_kind:     hidden_block_count_z
      - .offset:         156
        .size:           2
        .value_kind:     hidden_group_size_x
      - .offset:         158
        .size:           2
        .value_kind:     hidden_group_size_y
      - .offset:         160
        .size:           2
        .value_kind:     hidden_group_size_z
      - .offset:         162
        .size:           2
        .value_kind:     hidden_remainder_x
      - .offset:         164
        .size:           2
        .value_kind:     hidden_remainder_y
      - .offset:         166
        .size:           2
        .value_kind:     hidden_remainder_z
      - .offset:         184
        .size:           8
        .value_kind:     hidden_global_offset_x
      - .offset:         192
        .size:           8
        .value_kind:     hidden_global_offset_y
      - .offset:         200
        .size:           8
        .value_kind:     hidden_global_offset_z
      - .offset:         208
        .size:           2
        .value_kind:     hidden_grid_dims
      - .offset:         232
        .size:           8
        .value_kind:     hidden_multigrid_sync_arg
      - .offset:         264
        .size:           4
        .value_kind:     hidden_dynamic_lds_size
    .group_segment_fixed_size: 0
    .kernarg_segment_align: 8
    .kernarg_segment_size: 400
    .language:       OpenCL C
    .language_version:
      - 2
      - 0
    .max_flat_workgroup_size: 512
    .name:           _Z8mega_fwd6Params
    .private_segment_fixed_size: 0
    .sgpr_count:     108
    .sgpr_spill_count: 129
    .symbol:         _Z8mega_fwd6Params.kd
    .uniform_work_group_size: 1
    .uses_dynamic_stack: false
    .vgpr_count:     256
    .vgpr_spill_count: 0
    .wavefront_size: 64
